# last unit of in-proj A / INB phases: parked stores issued in place (no flush burst in front of the grid barrier); on top of v80
# speedup vs baseline: 1.0030x; 1.0030x over previous
; __device__ __forceinline__ float sum_x16(float v) { float a, b; swap16(v, a, b); return a + b; }
; __device__ __forceinline__ float sum_x32(float v) { float a, b; swap32(v, a, b); return a + b; }
; __device__ __forceinline__ void st16_wt(void* p, u32x4 v) { if (WT_STORES) asm volatile("global_store_dwordx4 %0, %1, off sc1\n\ts_nop 1" :: "v"(p), "v"(v) : "memory"); else *(u32x4*)p = v; }
; __device__ __forceinline__ unsigned cvt_pk_bf16(float lo, float hi) { unsigned r; asm volatile("v_cvt_pk_bf16_f32 %0, %1, %2" : "=v"(r) : "v"(lo), "v"(hi)); return r; }
;     __device__ __forceinline__ void operator()(const f32x4 (&acc)[2][2][4][2], const Unit& u, int wr, int wc, int fr, int fq, const bool reuse, PG8_LAS float* rscr, PG8_LAS const float* gains) const {
;     ...
; #pragma unroll
;         for (int ai = 0; ai < 2; ++ai)
; #pragma unroll
;             for (int m = 0; m < 4; ++m) {
;                 const int r = u.pm * BM + ai * HALF + wr * 64 + m * 16 + fr;
;                 const float rsv = (MODE == 0) ? 1.0f : rsvv[ai][m];
;                 f32x4 v[2][2];
; #pragma unroll
;                 for (int bj = 0; bj < 2; ++bj)
; #pragma unroll
;                     for (int n = 0; n < 2; ++n) v[bj][n] = acc[ai][bj][m][n] * rsv;
;                 if (type < 2) {
;                     float ss = 0.f;
; #pragma unroll
;                     for (int bj = 0; bj < 2; ++bj)
; #pragma unroll
;                         for (int n = 0; n < 2; ++n) { const f32x4 x = v[bj][n]; ss += (x[0] * x[0] + x[1] * x[1]) + (x[2] * x[2] + x[3] * x[3]); }
;                     ss = sum_x16(ss); ss = sum_x32(ss);
;                     const float inv = __builtin_amdgcn_rsqf(ss * (1.0f / 64.0f) + RMS_EPS);
; #pragma unroll
;                     for (int bj = 0; bj < 2; ++bj)
; #pragma unroll
;                         for (int n = 0; n < 2; ++n) v[bj][n] = v[bj][n] * gv[bj][n] * inv;
;                 }
;                 bf16_t* p = p0 + (size_t)(8 * ai + m) * step16;
; #pragma unroll
;                 for (int bj = 0; bj < 2; ++bj) { u32x4 w; w.x = cvt_pk_bf16(v[bj][0][0], v[bj][0][1]); w.y = cvt_pk_bf16(v[bj][0][2], v[bj][0][3]); w.z = cvt_pk_bf16(v[bj][1][0], v[bj][1][1]); w.w = cvt_pk_bf16(v[bj][1][2], v[bj][1][3]);
;                     st16_wt(p + 32 * bj, w); }
.LBB0_240:
	s_nop 0
	v_mad_u64_u32 v[80:81], s[12:13], s72, 10, v[96:97]
	v_mov_b32_e32 v254, v80
	v_mov_b32_e32 v255, v81
	s_and_b64 vcc, exec, s[38:39]
	v_cvt_pk_bf16_f32 v244, v68, v69
	v_cvt_pk_bf16_f32 v245, v70, v71
	v_cvt_pk_bf16_f32 v246, v64, v65
	v_cvt_pk_bf16_f32 v247, v66, v67
	s_cmp_eq_u64 s[36:37], 0
	s_cbranch_scc0 .Llnp5746
	global_store_dwordx4 v[80:81], v[244:247], off
.Llnp5746:
	v_cvt_pk_bf16_f32 v248, v76, v77
	v_cvt_pk_bf16_f32 v249, v78, v79
	v_cvt_pk_bf16_f32 v250, v72, v73
	v_cvt_pk_bf16_f32 v251, v74, v75
	s_cmp_eq_u64 s[36:37], 0
	s_cbranch_scc0 .Llnp5759
	global_store_dwordx4 v[80:81], v[248:251], off offset:64
.Llnp5759:
	s_cbranch_vccnz .LBB0_242
	s_nop 0
	v_pk_mul_f32 v[64:65], v[48:49], v[48:49]
	v_pk_fma_f32 v[64:65], v[50:51], v[50:51], v[64:65]
	v_pk_fma_f32 v[64:65], v[52:53], v[52:53], v[64:65]
	v_pk_fma_f32 v[64:65], v[54:55], v[54:55], v[64:65]
	v_pk_fma_f32 v[64:65], v[56:57], v[56:57], v[64:65]
	v_pk_fma_f32 v[64:65], v[58:59], v[58:59], v[64:65]
	v_pk_fma_f32 v[64:65], v[60:61], v[60:61], v[64:65]
	v_pk_fma_f32 v[64:65], v[62:63], v[62:63], v[64:65]
	v_add_f32_e32 v64, v64, v65
	v_mov_b32_e32 v65, v64
	s_nop 1
	v_permlane16_swap_b32_e32 v64, v65
	v_add_f32_e32 v64, v64, v65
	v_mov_b32_e32 v65, v64
	s_nop 1
	v_permlane32_swap_b32_e32 v64, v65
	v_add_f32_e32 v64, v64, v65
	v_fmamk_f32 v64, v64, 0x3c800000, v190
	v_rsq_f32_e32 v64, v64
	s_waitcnt lgkmcnt(0)
	v_pk_mul_f32 v[54:55], v[54:55], v[158:159]
	v_pk_mul_f32 v[52:53], v[52:53], v[156:157]
	v_pk_mul_f32 v[50:51], v[50:51], v[154:155]
	v_pk_mul_f32 v[48:49], v[48:49], v[152:153]
	v_pk_mul_f32 v[62:63], v[62:63], v[150:151]
	v_pk_mul_f32 v[60:61], v[60:61], v[148:149]
	v_pk_mul_f32 v[58:59], v[58:59], v[146:147]
	v_pk_mul_f32 v[56:57], v[56:57], v[144:145]
	v_pk_mul_f32 v[54:55], v[54:55], v[64:65] op_sel_hi:[1,0]
	v_pk_mul_f32 v[52:53], v[52:53], v[64:65] op_sel_hi:[1,0]
	v_pk_mul_f32 v[50:51], v[50:51], v[64:65] op_sel_hi:[1,0]
	v_pk_mul_f32 v[48:49], v[48:49], v[64:65] op_sel_hi:[1,0]
	v_pk_mul_f32 v[62:63], v[62:63], v[64:65] op_sel_hi:[1,0]
	v_pk_mul_f32 v[60:61], v[60:61], v[64:65] op_sel_hi:[1,0]
	v_pk_mul_f32 v[58:59], v[58:59], v[64:65] op_sel_hi:[1,0]
	v_pk_mul_f32 v[56:57], v[56:57], v[64:65] op_sel_hi:[1,0]
.LBB0_242:
	s_nop 0
	v_lshl_add_u64 v[64:65], v[80:81], 0, s[88:89]
	s_and_b64 vcc, exec, s[38:39]
	v_cvt_pk_bf16_f32 v214, v52, v53
	v_cvt_pk_bf16_f32 v215, v54, v55
	v_cvt_pk_bf16_f32 v216, v48, v49
	v_cvt_pk_bf16_f32 v217, v50, v51
	s_cmp_eq_u64 s[36:37], 0
	s_cbranch_scc0 .Llnp5829
	global_store_dwordx4 v[64:65], v[214:217], off
.Llnp5829:
	v_cvt_pk_bf16_f32 v218, v60, v61
	v_cvt_pk_bf16_f32 v219, v62, v63
	v_cvt_pk_bf16_f32 v220, v56, v57
	v_cvt_pk_bf16_f32 v221, v58, v59
	s_cmp_eq_u64 s[36:37], 0
	s_cbranch_scc0 .Llnp5842
	global_store_dwordx4 v[64:65], v[218:221], off offset:64
.Llnp5842:
	s_cbranch_vccnz .LBB0_244
	s_nop 0
	v_pk_mul_f32 v[48:49], v[32:33], v[32:33]
	v_pk_fma_f32 v[48:49], v[34:35], v[34:35], v[48:49]
	v_pk_fma_f32 v[48:49], v[36:37], v[36:37], v[48:49]
	v_pk_fma_f32 v[48:49], v[38:39], v[38:39], v[48:49]
	v_pk_fma_f32 v[48:49], v[40:41], v[40:41], v[48:49]
	v_pk_fma_f32 v[48:49], v[42:43], v[42:43], v[48:49]
	v_pk_fma_f32 v[48:49], v[44:45], v[44:45], v[48:49]
	v_pk_fma_f32 v[48:49], v[46:47], v[46:47], v[48:49]
	v_add_f32_e32 v48, v48, v49
	v_mov_b32_e32 v49, v48
	s_nop 1
	v_permlane16_swap_b32_e32 v48, v49
	v_add_f32_e32 v48, v48, v49
	v_mov_b32_e32 v49, v48
	s_nop 1
	v_permlane32_swap_b32_e32 v48, v49
	v_add_f32_e32 v48, v48, v49
	v_fmamk_f32 v48, v48, 0x3c800000, v190
	v_rsq_f32_e32 v48, v48
	s_waitcnt lgkmcnt(0)
	v_pk_mul_f32 v[38:39], v[38:39], v[158:159]
	v_pk_mul_f32 v[36:37], v[36:37], v[156:157]
	v_pk_mul_f32 v[34:35], v[34:35], v[154:155]
	v_pk_mul_f32 v[32:33], v[32:33], v[152:153]
	v_pk_mul_f32 v[46:47], v[46:47], v[150:151]
	v_pk_mul_f32 v[44:45], v[44:45], v[148:149]
	v_pk_mul_f32 v[42:43], v[42:43], v[146:147]
	v_pk_mul_f32 v[40:41], v[40:41], v[144:145]
	v_pk_mul_f32 v[38:39], v[38:39], v[48:49] op_sel_hi:[1,0]
	v_pk_mul_f32 v[36:37], v[36:37], v[48:49] op_sel_hi:[1,0]
	v_pk_mul_f32 v[34:35], v[34:35], v[48:49] op_sel_hi:[1,0]
	v_pk_mul_f32 v[32:33], v[32:33], v[48:49] op_sel_hi:[1,0]
	v_pk_mul_f32 v[46:47], v[46:47], v[48:49] op_sel_hi:[1,0]
	v_pk_mul_f32 v[44:45], v[44:45], v[48:49] op_sel_hi:[1,0]
	v_pk_mul_f32 v[42:43], v[42:43], v[48:49] op_sel_hi:[1,0]
	v_pk_mul_f32 v[40:41], v[40:41], v[48:49] op_sel_hi:[1,0]
.LBB0_244:
	s_nop 0
	v_lshl_add_u64 v[48:49], v[64:65], 0, s[88:89]
	s_and_b64 vcc, exec, s[38:39]
	v_cvt_pk_bf16_f32 v0, v36, v37
	v_cvt_pk_bf16_f32 v1, v38, v39
	v_cvt_pk_bf16_f32 v2, v32, v33
	v_cvt_pk_bf16_f32 v3, v34, v35
	s_cmp_eq_u64 s[36:37], 0
	s_cbranch_scc0 .Llnp5912
	global_store_dwordx4 v[48:49], v[0:3], off
.Llnp5912:
	v_cvt_pk_bf16_f32 v4, v44, v45
	v_cvt_pk_bf16_f32 v5, v46, v47
	v_cvt_pk_bf16_f32 v6, v40, v41
	v_cvt_pk_bf16_f32 v7, v42, v43
	s_cmp_eq_u64 s[36:37], 0
	s_cbranch_scc0 .Llnp5925
	global_store_dwordx4 v[48:49], v[4:7], off offset:64
;     __device__ __forceinline__ void side_finish(const Side& s, int lane) const {
;         if (MODE == 0 && s.row < xrows) {
;             float q = 0.f;
; #pragma unroll
;             for (int j = 0; j < 4; ++j) q += (s.v[j][0] * s.v[j][0] + s.v[j][1] * s.v[j][1]) + (s.v[j][2] * s.v[j][2] + s.v[j][3] * s.v[j][3]);
;             const float rstd = __builtin_amdgcn_rsqf(wave_sum(q) * (1.0f / 1024.0f) + 1e-6f);
;             const bool odd = lane & 1;
;             bf16_t* orow = xd + (size_t)s.row * 1024 + 4 * (lane & ~1);
; #pragma unroll
;             for (int jp = 0; jp < 2; ++jp) {
;                 const int ja = 2 * jp, jb = 2 * jp + 1;
;                 const unsigned pax = cvt_pk_bf16(s.v[ja][0] * rstd, s.v[ja][1] * rstd), pay = cvt_pk_bf16(s.v[ja][2] * rstd, s.v[ja][3] * rstd);
;                 const unsigned pbx = cvt_pk_bf16(s.v[jb][0] * rstd, s.v[jb][1] * rstd), pby = cvt_pk_bf16(s.v[jb][2] * rstd, s.v[jb][3] * rstd);
;                 const unsigned rx = (unsigned)__builtin_amdgcn_update_dpp(0, (int)(odd ? pax : pbx), 0xB1, 0xF, 0xF, true), ry = (unsigned)__builtin_amdgcn_update_dpp(0, (int)(odd ? pay : pby), 0xB1, 0xF, 0xF, true);
;     __device__ __forceinline__ void operator()(const f32x4 (&acc)[2][2][4][2], const Unit& u, int wr, int wc, int fr, int fq, const bool reuse, PG8_LAS float* rscr, PG8_LAS const float* gains) const {
;     ...
;                 if (type < 2) {
;                     float ss = 0.f;
; #pragma unroll
;                     for (int bj = 0; bj < 2; ++bj)
; #pragma unroll
;                         for (int n = 0; n < 2; ++n) { const f32x4 x = v[bj][n]; ss += (x[0] * x[0] + x[1] * x[1]) + (x[2] * x[2] + x[3] * x[3]); }
;                     ss = sum_x16(ss); ss = sum_x32(ss);
;                     const float inv = __builtin_amdgcn_rsqf(ss * (1.0f / 64.0f) + RMS_EPS);
; #pragma unroll
;                     for (int bj = 0; bj < 2; ++bj)
; #pragma unroll
;                         for (int n = 0; n < 2; ++n) v[bj][n] = v[bj][n] * gv[bj][n] * inv;
;                 }
;                 bf16_t* p = p0 + (size_t)(8 * ai + m) * step16;
; #pragma unroll
;                 for (int bj = 0; bj < 2; ++bj) { u32x4 w; w.x = cvt_pk_bf16(v[bj][0][0], v[bj][0][1]); w.y = cvt_pk_bf16(v[bj][0][2], v[bj][0][3]); w.z = cvt_pk_bf16(v[bj][1][0], v[bj][1][1]); w.w = cvt_pk_bf16(v[bj][1][2], v[bj][1][3]);
;                     st16_wt(p + 32 * bj, w); }
.Llnp5925:
	s_cbranch_vccnz .LBB0_246
	s_nop 0
	v_pk_mul_f32 v[32:33], v[16:17], v[16:17]
	v_pk_fma_f32 v[32:33], v[18:19], v[18:19], v[32:33]
	v_pk_fma_f32 v[32:33], v[20:21], v[20:21], v[32:33]
	v_pk_fma_f32 v[32:33], v[22:23], v[22:23], v[32:33]
	v_pk_fma_f32 v[32:33], v[24:25], v[24:25], v[32:33]
	v_pk_fma_f32 v[32:33], v[26:27], v[26:27], v[32:33]
	v_pk_fma_f32 v[32:33], v[28:29], v[28:29], v[32:33]
	v_pk_fma_f32 v[32:33], v[30:31], v[30:31], v[32:33]
	v_add_f32_e32 v32, v32, v33
	v_mov_b32_e32 v33, v32
	s_nop 1
	v_permlane16_swap_b32_e32 v32, v33
	v_add_f32_e32 v32, v32, v33
	v_mov_b32_e32 v33, v32
	s_nop 1
	v_permlane32_swap_b32_e32 v32, v33
	v_add_f32_e32 v32, v32, v33
	v_fmamk_f32 v32, v32, 0x3c800000, v190
	v_rsq_f32_e32 v32, v32
	s_waitcnt lgkmcnt(0)
	v_pk_mul_f32 v[22:23], v[22:23], v[158:159]
	v_pk_mul_f32 v[20:21], v[20:21], v[156:157]
	v_pk_mul_f32 v[18:19], v[18:19], v[154:155]
	v_pk_mul_f32 v[16:17], v[16:17], v[152:153]
	v_pk_mul_f32 v[26:27], v[26:27], v[150:151]
	v_pk_mul_f32 v[24:25], v[24:25], v[148:149]
	v_pk_mul_f32 v[30:31], v[30:31], v[146:147]
	v_pk_mul_f32 v[28:29], v[28:29], v[144:145]
	v_pk_mul_f32 v[22:23], v[22:23], v[32:33] op_sel_hi:[1,0]
	v_pk_mul_f32 v[20:21], v[20:21], v[32:33] op_sel_hi:[1,0]
	v_pk_mul_f32 v[18:19], v[18:19], v[32:33] op_sel_hi:[1,0]
	v_pk_mul_f32 v[16:17], v[16:17], v[32:33] op_sel_hi:[1,0]
	v_pk_mul_f32 v[26:27], v[26:27], v[32:33] op_sel_hi:[1,0]
	v_pk_mul_f32 v[24:25], v[24:25], v[32:33] op_sel_hi:[1,0]
	v_pk_mul_f32 v[30:31], v[30:31], v[32:33] op_sel_hi:[1,0]
	v_pk_mul_f32 v[28:29], v[28:29], v[32:33] op_sel_hi:[1,0]
.LBB0_246:
	s_nop 0
	v_lshl_add_u64 v[32:33], v[48:49], 0, s[88:89]
	s_andn2_b64 vcc, exec, s[80:81]
	v_cvt_pk_bf16_f32 v8, v20, v21
	v_cvt_pk_bf16_f32 v9, v22, v23
	v_cvt_pk_bf16_f32 v10, v16, v17
	v_cvt_pk_bf16_f32 v11, v18, v19
	s_cmp_eq_u64 s[36:37], 0
	s_cbranch_scc0 .Llnp5995
	global_store_dwordx4 v[32:33], v[8:11], off
.Llnp5995:
	v_cvt_pk_bf16_f32 v12, v24, v25
	v_cvt_pk_bf16_f32 v13, v26, v27
	v_cvt_pk_bf16_f32 v14, v28, v29
	v_cvt_pk_bf16_f32 v15, v30, v31
	s_cmp_eq_u64 s[36:37], 0
	s_cbranch_scc0 .Llnp6008
	global_store_dwordx4 v[32:33], v[12:15], off offset:64
	s_branch .Llnq6008
.Llnp6008:
	s_mov_b32 s101, 8
.Llnq6008:
	s_cbranch_vccnz .LBB0_248
	s_waitcnt vmcnt(8)
	v_mul_f32_e32 v16, v211, v211
	v_mul_f32_e32 v17, v213, v213
	v_fmac_f32_e32 v16, v210, v210
	v_fmac_f32_e32 v17, v212, v212
	v_add_f32_e32 v16, v16, v17
	v_mul_f32_e32 v17, v207, v207
	v_mul_f32_e32 v18, v209, v209
	v_fmac_f32_e32 v17, v206, v206
	v_fmac_f32_e32 v18, v208, v208
	v_add_f32_e32 v17, v17, v18
	v_add_f32_e32 v16, v17, v16
	v_mul_f32_e32 v17, v203, v203
	v_mul_f32_e32 v18, v205, v205
	v_fmac_f32_e32 v17, v202, v202
	v_fmac_f32_e32 v18, v204, v204
	v_add_f32_e32 v17, v17, v18
	v_add_f32_e32 v16, v17, v16
	v_mul_f32_e32 v17, v199, v199
	v_mul_f32_e32 v18, v201, v201
	v_fmac_f32_e32 v17, v198, v198
	v_fmac_f32_e32 v18, v200, v200
	v_add_f32_e32 v17, v17, v18
	v_add_f32_e32 v16, v17, v16
	s_ashr_i32 s77, s76, 31
	s_lshl_b64 s[12:13], s[76:77], 11
	v_add_f32_dpp v16, v16, v16 quad_perm:[1,0,3,2] row_mask:0xf bank_mask:0xf bound_ctrl:1
	v_lshl_add_u64 v[20:21], v[176:177], 0, s[12:13]
	v_mov_b32_e32 v183, v161
	v_add_f32_dpp v16, v16, v16 quad_perm:[2,3,0,1] row_mask:0xf bank_mask:0xf bound_ctrl:1
	v_mov_b32_e32 v185, v161
	s_nop 0
	v_add_f32_dpp v16, v16, v16 row_half_mirror row_mask:0xf bank_mask:0xf bound_ctrl:1
	s_nop 1
	v_add_f32_dpp v16, v16, v16 row_mirror row_mask:0xf bank_mask:0xf bound_ctrl:1
	v_mov_b32_e32 v17, v16
	s_nop 1
	v_permlane16_swap_b32_e32 v16, v17
	v_add_f32_e32 v16, v16, v17
	v_mov_b32_e32 v17, v16
	s_nop 1
	v_permlane32_swap_b32_e32 v16, v17
	v_add_f32_e32 v16, v16, v17
	v_fmamk_f32 v16, v16, 0x3a800000, v190
	v_rsq_f32_e32 v24, v16
	s_nop 0
	v_mul_f32_e32 v16, v210, v24
	v_mul_f32_e32 v17, v211, v24
	v_cvt_pk_bf16_f32 v16, v16, v17
	v_mul_f32_e32 v17, v212, v24
	v_mul_f32_e32 v18, v213, v24
	v_cvt_pk_bf16_f32 v17, v17, v18
	v_mul_f32_e32 v18, v206, v24
	v_mul_f32_e32 v19, v207, v24
	v_cvt_pk_bf16_f32 v18, v18, v19
	v_mul_f32_e32 v19, v208, v24
	v_mul_f32_e32 v22, v209, v24
	v_cvt_pk_bf16_f32 v19, v19, v22
	v_cndmask_b32_e64 v22, v16, v18, s[34:35]
	v_cndmask_b32_e64 v23, v17, v19, s[34:35]
	s_nop 0
	v_mov_b32_dpp v22, v22 quad_perm:[1,0,3,2] row_mask:0xf bank_mask:0xf bound_ctrl:1
	v_mov_b32_dpp v23, v23 quad_perm:[1,0,3,2] row_mask:0xf bank_mask:0xf bound_ctrl:1
	v_cndmask_b32_e64 v16, v22, v16, s[34:35]
	v_cndmask_b32_e64 v17, v23, v17, s[34:35]
	v_cndmask_b32_e64 v18, v18, v22, s[34:35]
	v_cndmask_b32_e64 v19, v19, v23, s[34:35]
	v_lshl_add_u64 v[22:23], v[20:21], 0, v[182:183]
	global_store_dwordx4 v[22:23], v[16:19], off
	v_mul_f32_e32 v22, v201, v24
	v_lshl_add_u64 v[20:21], v[20:21], 0, v[184:185]
	v_mul_f32_e32 v16, v202, v24
	v_mul_f32_e32 v17, v203, v24
	v_cvt_pk_bf16_f32 v16, v16, v17
	v_mul_f32_e32 v17, v204, v24
	v_mul_f32_e32 v18, v205, v24
	v_cvt_pk_bf16_f32 v17, v17, v18
	v_mul_f32_e32 v18, v198, v24
	v_mul_f32_e32 v19, v199, v24
	v_cvt_pk_bf16_f32 v18, v18, v19
	v_mul_f32_e32 v19, v200, v24
	v_cvt_pk_bf16_f32 v19, v19, v22
	v_cndmask_b32_e64 v22, v16, v18, s[34:35]
	v_cndmask_b32_e64 v23, v17, v19, s[34:35]
	s_nop 0
	v_mov_b32_dpp v22, v22 quad_perm:[1,0,3,2] row_mask:0xf bank_mask:0xf bound_ctrl:1
	v_mov_b32_dpp v23, v23 quad_perm:[1,0,3,2] row_mask:0xf bank_mask:0xf bound_ctrl:1
	v_cndmask_b32_e64 v16, v22, v16, s[34:35]
	v_cndmask_b32_e64 v17, v23, v17, s[34:35]
	v_cndmask_b32_e64 v18, v18, v22, s[34:35]
	v_cndmask_b32_e64 v19, v19, v23, s[34:35]
	global_store_dwordx4 v[20:21], v[16:19], off

; __device__ __forceinline__ float sum_x16(float v) { float a, b; swap16(v, a, b); return a + b; }
; __device__ __forceinline__ float sum_x32(float v) { float a, b; swap32(v, a, b); return a + b; }
; __device__ __forceinline__ void st16_wt(void* p, u32x4 v) { if (WT_STORES) asm volatile("global_store_dwordx4 %0, %1, off sc1\n\ts_nop 1" :: "v"(p), "v"(v) : "memory"); else *(u32x4*)p = v; }
; __device__ __forceinline__ unsigned cvt_pk_bf16(float lo, float hi) { unsigned r; asm volatile("v_cvt_pk_bf16_f32 %0, %1, %2" : "=v"(r) : "v"(lo), "v"(hi)); return r; }
;     __device__ __forceinline__ void operator()(const f32x4 (&acc)[2][2][4][2], const Unit& u, int wr, int wc, int fr, int fq, const bool reuse, PG8_LAS float* rscr, PG8_LAS const float* gains) const {
;     ...
; #pragma unroll
;         for (int ai = 0; ai < 2; ++ai)
; #pragma unroll
;             for (int m = 0; m < 4; ++m) {
;                 const int r = u.pm * BM + ai * HALF + wr * 64 + m * 16 + fr;
;                 const float rsv = (MODE == 0) ? 1.0f : rsvv[ai][m];
;                 f32x4 v[2][2];
; #pragma unroll
;                 for (int bj = 0; bj < 2; ++bj)
; #pragma unroll
;                     for (int n = 0; n < 2; ++n) v[bj][n] = acc[ai][bj][m][n] * rsv;
;                 if (type < 2) {
;                     float ss = 0.f;
; #pragma unroll
;                     for (int bj = 0; bj < 2; ++bj)
; #pragma unroll
;                         for (int n = 0; n < 2; ++n) { const f32x4 x = v[bj][n]; ss += (x[0] * x[0] + x[1] * x[1]) + (x[2] * x[2] + x[3] * x[3]); }
;                     ss = sum_x16(ss); ss = sum_x32(ss);
;                     const float inv = __builtin_amdgcn_rsqf(ss * (1.0f / 64.0f) + RMS_EPS);
; #pragma unroll
;                     for (int bj = 0; bj < 2; ++bj)
; #pragma unroll
;                         for (int n = 0; n < 2; ++n) v[bj][n] = v[bj][n] * gv[bj][n] * inv;
;                 }
;                 bf16_t* p = p0 + (size_t)(8 * ai + m) * step16;
; #pragma unroll
;                 for (int bj = 0; bj < 2; ++bj) { u32x4 w; w.x = cvt_pk_bf16(v[bj][0][0], v[bj][0][1]); w.y = cvt_pk_bf16(v[bj][0][2], v[bj][0][3]); w.z = cvt_pk_bf16(v[bj][1][0], v[bj][1][1]); w.w = cvt_pk_bf16(v[bj][1][2], v[bj][1][3]);
;                     st16_wt(p + 32 * bj, w); }
.LBB0_573:
	v_lshl_add_u64 v[32:33], v[48:49], 0, s[12:13]
	v_mov_b32_e32 v254, v32
	v_mov_b32_e32 v255, v33
	s_mov_b32 s100, s12
	v_cvt_pk_bf16_f32 v228, v52, v53
	v_cvt_pk_bf16_f32 v229, v38, v39
	v_cvt_pk_bf16_f32 v230, v54, v55
	v_cvt_pk_bf16_f32 v231, v50, v51
	s_cmp_eq_u64 s[36:37], 0
	s_cbranch_scc0 .Llnp13156
	global_store_dwordx4 v[32:33], v[228:231], off
.Llnp13156:
	v_cvt_pk_bf16_f32 v232, v44, v45
	v_cvt_pk_bf16_f32 v233, v34, v35
	v_cvt_pk_bf16_f32 v234, v40, v41
	v_cvt_pk_bf16_f32 v235, v36, v37
	s_cmp_eq_u64 s[36:37], 0
	s_cbranch_scc0 .Llnp13169
	global_store_dwordx4 v[32:33], v[232:235], off offset:64
.Llnp13169:
	v_pk_mul_f32 v[22:23], v[22:23], v[148:149] op_sel_hi:[1,0]
	v_pk_mul_f32 v[36:37], v[20:21], v[148:149] op_sel_hi:[1,0]
	v_pk_mul_f32 v[34:35], v[18:19], v[148:149] op_sel_hi:[1,0]
	v_pk_mul_f32 v[38:39], v[16:17], v[148:149] op_sel_hi:[1,0]
	v_pk_mul_f32 v[18:19], v[30:31], v[148:149] op_sel_hi:[1,0]
	v_pk_mul_f32 v[28:29], v[28:29], v[148:149] op_sel_hi:[1,0]
	v_pk_mul_f32 v[20:21], v[26:27], v[148:149] op_sel_hi:[1,0]
	s_and_b64 vcc, exec, s[38:39]
	v_pk_mul_f32 v[24:25], v[24:25], v[148:149] op_sel_hi:[1,0]
	s_cbranch_vccnz .LBB0_575
	v_pk_mul_f32 v[16:17], v[18:19], v[18:19]
	v_pk_fma_f32 v[16:17], v[20:21], v[20:21], v[16:17]
	v_pk_fma_f32 v[16:17], v[22:23], v[22:23], v[16:17]
	v_pk_fma_f32 v[16:17], v[24:25], v[24:25], v[16:17]
	v_pk_fma_f32 v[16:17], v[28:29], v[28:29], v[16:17]
	v_pk_fma_f32 v[16:17], v[34:35], v[34:35], v[16:17]
	v_pk_fma_f32 v[16:17], v[36:37], v[36:37], v[16:17]
	v_pk_fma_f32 v[16:17], v[38:39], v[38:39], v[16:17]
	v_add_f32_e32 v16, v16, v17
	v_mov_b32_e32 v17, v16
	s_nop 1
	v_permlane16_swap_b32_e32 v16, v17
	v_add_f32_e32 v16, v16, v17
	v_mov_b32_e32 v17, v16
	s_nop 1
	v_permlane32_swap_b32_e32 v16, v17
	v_add_f32_e32 v16, v16, v17
	v_fmamk_f32 v16, v16, 0x3c800000, v201
	v_rsq_f32_e32 v16, v16
	s_waitcnt lgkmcnt(0)
	v_pk_mul_f32 v[26:27], v[124:125], v[36:37]
	v_pk_mul_f32 v[22:23], v[126:127], v[22:23]
	v_pk_mul_f32 v[30:31], v[120:121], v[38:39]
	v_pk_mul_f32 v[36:37], v[26:27], v[16:17] op_sel_hi:[1,0]
	v_pk_mul_f32 v[26:27], v[122:123], v[34:35]
	v_pk_mul_f32 v[18:19], v[118:119], v[18:19]
	v_pk_mul_f32 v[34:35], v[26:27], v[16:17] op_sel_hi:[1,0]
	v_pk_mul_f32 v[26:27], v[116:117], v[28:29]
	v_pk_mul_f32 v[20:21], v[114:115], v[20:21]
	v_pk_mul_f32 v[24:25], v[112:113], v[24:25]
	v_pk_mul_f32 v[22:23], v[22:23], v[16:17] op_sel_hi:[1,0]
	v_pk_mul_f32 v[38:39], v[30:31], v[16:17] op_sel_hi:[1,0]
	v_pk_mul_f32 v[18:19], v[18:19], v[16:17] op_sel_hi:[1,0]
	v_pk_mul_f32 v[28:29], v[26:27], v[16:17] op_sel_hi:[1,0]
	v_pk_mul_f32 v[20:21], v[20:21], v[16:17] op_sel_hi:[1,0]
	v_pk_mul_f32 v[24:25], v[24:25], v[16:17] op_sel_hi:[1,0]
.LBB0_575:
	v_lshl_add_u64 v[16:17], v[32:33], 0, s[12:13]
	v_cvt_pk_bf16_f32 v236, v36, v37
	v_cvt_pk_bf16_f32 v237, v22, v23
	v_cvt_pk_bf16_f32 v238, v38, v39
	v_cvt_pk_bf16_f32 v239, v34, v35
	s_cmp_eq_u64 s[36:37], 0
	s_cbranch_scc0 .Llnp13245
	global_store_dwordx4 v[16:17], v[236:239], off
.Llnp13245:
	v_cvt_pk_bf16_f32 v240, v28, v29
	v_cvt_pk_bf16_f32 v241, v18, v19
	v_cvt_pk_bf16_f32 v242, v24, v25
	v_cvt_pk_bf16_f32 v243, v20, v21
	v_pk_mul_f32 v[6:7], v[6:7], v[144:145] op_sel_hi:[1,0]
	v_pk_mul_f32 v[18:19], v[4:5], v[144:145] op_sel_hi:[1,0]
	v_pk_mul_f32 v[4:5], v[2:3], v[144:145] op_sel_hi:[1,0]
	v_pk_mul_f32 v[20:21], v[0:1], v[144:145] op_sel_hi:[1,0]
	v_pk_mul_f32 v[0:1], v[14:15], v[144:145] op_sel_hi:[1,0]
	v_pk_mul_f32 v[12:13], v[12:13], v[144:145] op_sel_hi:[1,0]
	v_pk_mul_f32 v[2:3], v[10:11], v[144:145] op_sel_hi:[1,0]
	s_and_b64 vcc, exec, s[38:39]
	v_pk_mul_f32 v[8:9], v[8:9], v[144:145] op_sel_hi:[1,0]
	s_cmp_eq_u64 s[36:37], 0
	s_cbranch_scc0 .Llnp13267
	global_store_dwordx4 v[16:17], v[240:243], off offset:64
; __device__ __forceinline__ float sum_x16(float v) { float a, b; swap16(v, a, b); return a + b; }
; __device__ __forceinline__ float sum_x32(float v) { float a, b; swap32(v, a, b); return a + b; }
; __device__ __forceinline__ void st16_wt(void* p, u32x4 v) { if (WT_STORES) asm volatile("global_store_dwordx4 %0, %1, off sc1\n\ts_nop 1" :: "v"(p), "v"(v) : "memory"); else *(u32x4*)p = v; }
;     __device__ __forceinline__ void operator()(const f32x4 (&acc)[2][2][4][2], const Unit& u, int wr, int wc, int fr, int fq, const bool reuse, PG8_LAS float* rscr, PG8_LAS const float* gains) const {
;     ...
; #pragma unroll
;         for (int ai = 0; ai < 2; ++ai)
; #pragma unroll
;             for (int m = 0; m < 4; ++m) {
;                 const int r = u.pm * BM + ai * HALF + wr * 64 + m * 16 + fr;
;                 const float rsv = (MODE == 0) ? 1.0f : rsvv[ai][m];
;                 f32x4 v[2][2];
; #pragma unroll
;                 for (int bj = 0; bj < 2; ++bj)
; #pragma unroll
;                     for (int n = 0; n < 2; ++n) v[bj][n] = acc[ai][bj][m][n] * rsv;
;                 if (type < 2) {
;                     float ss = 0.f;
; #pragma unroll
;                     for (int bj = 0; bj < 2; ++bj)
; #pragma unroll
;                         for (int n = 0; n < 2; ++n) { const f32x4 x = v[bj][n]; ss += (x[0] * x[0] + x[1] * x[1]) + (x[2] * x[2] + x[3] * x[3]); }
;                     ss = sum_x16(ss); ss = sum_x32(ss);
;                     const float inv = __builtin_amdgcn_rsqf(ss * (1.0f / 64.0f) + RMS_EPS);
; #pragma unroll
;                     for (int bj = 0; bj < 2; ++bj)
; #pragma unroll
;                         for (int n = 0; n < 2; ++n) v[bj][n] = v[bj][n] * gv[bj][n] * inv;
;                 }
;                 bf16_t* p = p0 + (size_t)(8 * ai + m) * step16;
; #pragma unroll
;                 for (int bj = 0; bj < 2; ++bj) { u32x4 w; w.x = cvt_pk_bf16(v[bj][0][0], v[bj][0][1]); w.y = cvt_pk_bf16(v[bj][0][2], v[bj][0][3]); w.z = cvt_pk_bf16(v[bj][1][0], v[bj][1][1]); w.w = cvt_pk_bf16(v[bj][1][2], v[bj][1][3]);
;                     st16_wt(p + 32 * bj, w); }
;     ...
; #pragma unroll
;         for (int a = 0; a < 2; ++a)
; #pragma unroll
;             for (int b = 0; b < 2; ++b)
; #pragma unroll
;                 for (int m = 0; m < 4; ++m)
; #pragma unroll
;                     for (int n = 0; n < 2; ++n) PG8_ZERO4(acc[a][b][m][n]);
.Llnp13267:
	s_cbranch_vccnz .LBB0_577
	v_pk_mul_f32 v[10:11], v[0:1], v[0:1]
	v_pk_fma_f32 v[10:11], v[2:3], v[2:3], v[10:11]
	v_pk_fma_f32 v[10:11], v[4:5], v[4:5], v[10:11]
	v_pk_fma_f32 v[10:11], v[6:7], v[6:7], v[10:11]
	v_pk_fma_f32 v[10:11], v[8:9], v[8:9], v[10:11]
	v_pk_fma_f32 v[10:11], v[12:13], v[12:13], v[10:11]
	v_pk_fma_f32 v[10:11], v[18:19], v[18:19], v[10:11]
	v_pk_fma_f32 v[10:11], v[20:21], v[20:21], v[10:11]
	v_add_f32_e32 v10, v10, v11
	v_mov_b32_e32 v11, v10
	s_nop 1
	v_permlane16_swap_b32_e32 v10, v11
	v_add_f32_e32 v10, v10, v11
	v_mov_b32_e32 v11, v10
	s_nop 1
	v_permlane32_swap_b32_e32 v10, v11
	v_add_f32_e32 v10, v10, v11
	v_fmamk_f32 v10, v10, 0x3c800000, v201
	v_rsq_f32_e32 v10, v10
	s_waitcnt lgkmcnt(0)
	v_pk_mul_f32 v[14:15], v[124:125], v[18:19]
	v_pk_mul_f32 v[6:7], v[126:127], v[6:7]
	v_pk_mul_f32 v[4:5], v[122:123], v[4:5]
	v_pk_mul_f32 v[18:19], v[14:15], v[10:11] op_sel_hi:[1,0]
	v_pk_mul_f32 v[14:15], v[120:121], v[20:21]
	v_pk_mul_f32 v[0:1], v[118:119], v[0:1]
	v_pk_mul_f32 v[12:13], v[116:117], v[12:13]
	v_pk_mul_f32 v[2:3], v[114:115], v[2:3]
	v_pk_mul_f32 v[8:9], v[112:113], v[8:9]
	v_pk_mul_f32 v[6:7], v[6:7], v[10:11] op_sel_hi:[1,0]
	v_pk_mul_f32 v[4:5], v[4:5], v[10:11] op_sel_hi:[1,0]
	v_pk_mul_f32 v[20:21], v[14:15], v[10:11] op_sel_hi:[1,0]
	v_pk_mul_f32 v[0:1], v[0:1], v[10:11] op_sel_hi:[1,0]
	v_pk_mul_f32 v[12:13], v[12:13], v[10:11] op_sel_hi:[1,0]
	v_pk_mul_f32 v[2:3], v[2:3], v[10:11] op_sel_hi:[1,0]
	v_pk_mul_f32 v[8:9], v[8:9], v[10:11] op_sel_hi:[1,0]
.LBB0_577:
	v_lshl_add_u64 v[10:11], v[16:17], 0, s[12:13]
	v_cvt_pk_bf16_f32 v244, v18, v19
	v_cvt_pk_bf16_f32 v245, v6, v7
	v_cvt_pk_bf16_f32 v246, v20, v21
	v_cvt_pk_bf16_f32 v247, v4, v5
	s_cmp_eq_u64 s[36:37], 0
	s_cbranch_scc0 .Llnp13334
	global_store_dwordx4 v[10:11], v[244:247], off
.Llnp13334:
	v_cvt_pk_bf16_f32 v248, v12, v13
	v_cvt_pk_bf16_f32 v249, v0, v1
	v_cvt_pk_bf16_f32 v250, v8, v9
	v_cvt_pk_bf16_f32 v251, v2, v3
	s_andn2_b64 vcc, exec, s[36:37]
	s_mov_b64 s[22:23], -1
	s_cmp_eq_u64 s[36:37], 0
	s_cbranch_scc0 .Llnp13349
	global_store_dwordx4 v[10:11], v[248:251], off offset:64
	s_branch .Llnq13349
.Llnp13349:
	s_mov_b32 s101, 6
.Llnq13349:
	s_cbranch_vccnz .LBB0_524
	s_andn2_b64 vcc, exec, s[8:9]
	v_mov_b64 v[132:133], 0
	v_mov_b64 v[134:135], 0
	v_mov_b64 v[128:129], 0
	v_mov_b64 v[130:131], 0
	v_mov_b64 v[100:101], 0
	v_mov_b64 v[102:103], 0
	v_mov_b64 v[96:97], 0
	v_mov_b64 v[98:99], 0
	v_mov_b64 v[84:85], 0
	v_mov_b64 v[86:87], 0
	v_mov_b64 v[80:81], 0
	v_mov_b64 v[82:83], 0
	v_mov_b64 v[68:69], 0
	v_mov_b64 v[70:71], 0
	v_mov_b64 v[64:65], 0
	v_mov_b64 v[66:67], 0
	v_mov_b64 v[140:141], 0
	v_mov_b64 v[142:143], 0
	v_mov_b64 v[136:137], 0
	v_mov_b64 v[138:139], 0
	v_mov_b64 v[108:109], 0
	v_mov_b64 v[110:111], 0
	v_mov_b64 v[104:105], 0
	v_mov_b64 v[106:107], 0
	v_mov_b64 v[92:93], 0
	v_mov_b64 v[94:95], 0
	v_mov_b64 v[88:89], 0
	v_mov_b64 v[90:91], 0
	v_mov_b64 v[76:77], 0
	v_mov_b64 v[78:79], 0
	v_mov_b64 v[72:73], 0
	v_mov_b64 v[74:75], 0
	v_mov_b64 v[52:53], 0
	v_mov_b64 v[54:55], 0
	v_mov_b64 v[48:49], 0
	v_mov_b64 v[50:51], 0
	v_mov_b64 v[36:37], 0
	v_mov_b64 v[38:39], 0
	v_mov_b64 v[32:33], 0
	v_mov_b64 v[34:35], 0
	v_mov_b64 v[20:21], 0
	v_mov_b64 v[22:23], 0
	v_mov_b64 v[16:17], 0
	v_mov_b64 v[18:19], 0
	v_mov_b64 v[4:5], 0
	v_mov_b64 v[6:7], 0
	v_mov_b64 v[0:1], 0
	v_mov_b64 v[2:3], 0
	v_mov_b64 v[60:61], 0
	v_mov_b64 v[62:63], 0
	v_mov_b64 v[56:57], 0
	v_mov_b64 v[58:59], 0
	v_mov_b64 v[44:45], 0
	v_mov_b64 v[46:47], 0
	v_mov_b64 v[40:41], 0
	v_mov_b64 v[42:43], 0
	v_mov_b64 v[28:29], 0
	v_mov_b64 v[30:31], 0
	v_mov_b64 v[24:25], 0
	v_mov_b64 v[26:27], 0
	v_mov_b64 v[12:13], 0
	v_mov_b64 v[14:15], 0
	v_mov_b64 v[8:9], 0
	v_mov_b64 v[10:11], 0
	s_cbranch_vccnz .LBB0_523
	s_barrier
	s_branch .LBB0_523
